# speedup vs baseline: 1.0065x; 1.0065x over previous
; #define QK_FENCE() __builtin_amdgcn_sched_barrier(0x406)
; DI void partialSM(f32x16& p0, f32x16& p1, float& m_reg, float& mn, float& alpha) {
;     ...
;   else { mn = fmaxf(m_reg, pmax); alpha = __builtin_amdgcn_exp2f((m_reg - mn) * C); m_reg = mn; }
;   const float mnC = -mn * C;
; #pragma unroll
;   for (int r = 0; r < 16; ++r) p0[r] = fmaf(p0[r], C, mnC);
; #pragma unroll
;   for (int r = 0; r < 16; ++r) p1[r] = fmaf(p1[r], C, mnC);
; #pragma unroll
;   for (int r = 0; r < 16; ++r) p0[r] = __builtin_amdgcn_exp2f(p0[r]);
; }
; DI void finishSM(f32x16& p0, f32x16& p1, float alpha, float& l_reg, bf16x8& pa0, bf16x8& pa1, bf16x8& pa2, bf16x8& pa3) {
; #pragma unroll
;   for (int r = 0; r < 16; ++r) p1[r] = __builtin_amdgcn_exp2f(p1[r]);
;   float ps = 0;
; #pragma unroll
;   for (int r = 0; r < 16; ++r) ps += p0[r];
; #pragma unroll
;   for (int r = 0; r < 16; ++r) ps += p1[r];
;   { auto rr = __builtin_amdgcn_permlane32_swap(__float_as_uint(ps), __float_as_uint(ps), false, false);
;     ps = __uint_as_float(rr[0]) + __uint_as_float(rr[1]); }
;   l_reg = l_reg * alpha + ps;
; DI void qkt12(f32x16& p0, f32x16& p1, const char* Kt, const char* Rt, const int* ko, const int* ro, const bf16x8* qr) {
;   { const f32x16 z = {0.f, 0.f, 0.f, 0.f, 0.f, 0.f, 0.f, 0.f, 0.f, 0.f, 0.f, 0.f, 0.f, 0.f, 0.f, 0.f}; p0 = z; p1 = z; }
;   const char* kp[4] = {Kt + ko[0], Kt + ko[1], Kt + ko[2], Kt + ko[3]};
;   const char* rp[4] = {Rt + ro[0], Rt + ro[1], Rt + ro[2], Rt + ro[3]};
;   bf16x8 ka[2], kb[2];
;   ka[0] = *reinterpret_cast<const bf16x8*>(kp[0]); kb[0] = *reinterpret_cast<const bf16x8*>(kp[0] + 8192);
; #pragma unroll
;   for (int d0 = 0; d0 < 12; ++d0) {
;     if (d0 + 1 < 12) { const int d1 = d0 + 1;
;       if (d1 < 8) { ka[d1 & 1] = *reinterpret_cast<const bf16x8*>(kp[d1 & 3] + (d1 >> 2) * 128); kb[d1 & 1] = *reinterpret_cast<const bf16x8*>(kp[d1 & 3] + (d1 >> 2) * 128 + 8192); }
;       else { ka[d1 & 1] = *reinterpret_cast<const bf16x8*>(rp[d1 - 8]); kb[d1 & 1] = *reinterpret_cast<const bf16x8*>(rp[d1 - 8] + 4096); } }
;     QK_FENCE();
;     p0 = __builtin_amdgcn_mfma_f32_32x32x16_bf16(ka[d0 & 1], qr[d0], p0, 0, 0, 0);
;     p1 = __builtin_amdgcn_mfma_f32_32x32x16_bf16(kb[d0 & 1], qr[d0], p1, 0, 0, 0);
;     QK_FENCE();
;   }
.LBB0_128:
	s_add_i32 s2, s12, -1
	s_cmp_ge_u32 s2, s52
	s_cbranch_scc1 .Lattn_bb2_nodma
	v_cndmask_b32_e64 v160, v160, v187, s[38:39]
	s_add_i32 s2, s42, 0xa000
	s_cmp_lg_u32 s61, 2
	s_cselect_b32 s2, s2, 0
	s_add_i32 s6, s2, 16
	v_add_u32_e32 v213, s6, v176
	ds_read_b128 v[222:225], v213 offset:16384
	v_add_u32_e32 v230, s6, v179
	ds_read_b128 v[226:229], v213 offset:24576
	ds_read_b128 v[214:217], v230 offset:16384
	ds_read_b128 v[218:221], v230 offset:24576
	v_add_u32_e32 v231, s6, v180
	v_add_u32_e32 v234, s6, v181
	v_mul_f32_e32 v197, 0xbdd53b94, v160
	v_fmamk_f32 v161, v94, 0x3dd53b94, v197
	v_fmamk_f32 v194, v80, 0x3dd53b94, v197
	v_fmamk_f32 v196, v81, 0x3dd53b94, v197
	v_fmamk_f32 v192, v82, 0x3dd53b94, v197
	v_fmamk_f32 v195, v83, 0x3dd53b94, v197
	v_fmamk_f32 v187, v84, 0x3dd53b94, v197
	v_fmamk_f32 v193, v85, 0x3dd53b94, v197
	v_fmamk_f32 v169, v86, 0x3dd53b94, v197
	v_fmamk_f32 v190, v87, 0x3dd53b94, v197
	v_fmamk_f32 v166, v88, 0x3dd53b94, v197
	v_fmamk_f32 v168, v89, 0x3dd53b94, v197
	v_fmamk_f32 v164, v90, 0x3dd53b94, v197
	v_fmamk_f32 v167, v91, 0x3dd53b94, v197
	v_fmamk_f32 v162, v92, 0x3dd53b94, v197
	v_fmamk_f32 v165, v93, 0x3dd53b94, v197
	v_fmamk_f32 v163, v95, 0x3dd53b94, v197
	v_fmamk_f32 v208, v74, 0x3dd53b94, v197
	v_fmamk_f32 v209, v75, 0x3dd53b94, v197
	v_fmamk_f32 v198, v64, 0x3dd53b94, v197
	v_fmamk_f32 v199, v65, 0x3dd53b94, v197
	v_fmamk_f32 v200, v66, 0x3dd53b94, v197
	v_fmamk_f32 v201, v67, 0x3dd53b94, v197
	v_fmamk_f32 v202, v68, 0x3dd53b94, v197
	v_fmamk_f32 v203, v69, 0x3dd53b94, v197
	v_fmamk_f32 v204, v70, 0x3dd53b94, v197
	v_fmamk_f32 v205, v71, 0x3dd53b94, v197
	v_fmamk_f32 v206, v72, 0x3dd53b94, v197
	v_fmamk_f32 v207, v73, 0x3dd53b94, v197
	v_fmamk_f32 v210, v76, 0x3dd53b94, v197
	v_fmamk_f32 v211, v77, 0x3dd53b94, v197
	v_fmamk_f32 v212, v78, 0x3dd53b94, v197
	v_fmac_f32_e32 v197, 0x3dd53b94, v79
	v_exp_f32_e32 v161, v161
	s_waitcnt lgkmcnt(3)
	v_mfma_f32_32x32x16_bf16 v[80:95], v[222:225], v[134:137], 0
	v_exp_f32_e32 v194, v194
	v_exp_f32_e32 v196, v196
	v_exp_f32_e32 v192, v192
	s_waitcnt lgkmcnt(2)
	v_mfma_f32_32x32x16_bf16 v[64:79], v[226:229], v[134:137], 0
	ds_read_b128 v[222:225], v231 offset:16384
	ds_read_b128 v[226:229], v231 offset:24576
	v_exp_f32_e32 v195, v195
	v_exp_f32_e32 v187, v187
	v_exp_f32_e32 v193, v193
	s_waitcnt lgkmcnt(3)
	v_mfma_f32_32x32x16_bf16 v[80:95], v[214:217], v[130:133], v[80:95]
	v_add_u32_e32 v240, s44, v178
	v_exp_f32_e32 v169, v169
	v_readfirstlane_b32 s2, v240
	s_mov_b64 s[0:1], 0x1bc00100
	v_lshl_add_u64 v[238:239], v[158:159], 0, s[0:1]
	s_mov_b32 m0, s2
	v_exp_f32_e32 v190, v190
	global_load_lds_dwordx4 v[238:239], off
	s_waitcnt lgkmcnt(2)
	v_mfma_f32_32x32x16_bf16 v[64:79], v[218:221], v[130:133], v[64:79]
	ds_read_b128 v[214:217], v234 offset:16384
	ds_read_b128 v[218:221], v234 offset:24576
	v_exp_f32_e32 v166, v166
	v_exp_f32_e32 v168, v168
	v_exp_f32_e32 v164, v164
	s_waitcnt lgkmcnt(3)
	v_mfma_f32_32x32x16_bf16 v[80:95], v[222:225], v[126:129], v[80:95]
	v_exp_f32_e32 v167, v167
	v_exp_f32_e32 v162, v162
	v_exp_f32_e32 v165, v165
	s_waitcnt lgkmcnt(2)
	v_mfma_f32_32x32x16_bf16 v[64:79], v[226:229], v[126:129], v[64:79]
	ds_read_b128 v[222:225], v213 offset:16512
	ds_read_b128 v[226:229], v213 offset:24704
	v_add_u32_e32 v213, s6, v182
	v_exp_f32_e32 v163, v163
	v_exp_f32_e32 v198, v198
	s_waitcnt lgkmcnt(3)
	v_mfma_f32_32x32x16_bf16 v[80:95], v[214:217], v[114:117], v[80:95]
	v_add_u32_e32 v242, 0x2000, v240
	s_mov_b64 s[0:1], 0x1bc20100
	v_lshl_add_u64 v[238:239], v[158:159], 0, s[0:1]
	v_readfirstlane_b32 s2, v242
	s_mov_b32 m0, s2
	v_exp_f32_e32 v199, v199
	global_load_lds_dwordx4 v[238:239], off
	s_waitcnt lgkmcnt(2)
	v_mfma_f32_32x32x16_bf16 v[64:79], v[218:221], v[114:117], v[64:79]
	ds_read_b128 v[214:217], v230 offset:16512
	ds_read_b128 v[218:221], v230 offset:24704
	v_exp_f32_e32 v200, v200
	v_exp_f32_e32 v201, v201
	v_exp_f32_e32 v202, v202
	s_waitcnt lgkmcnt(3)
	v_mfma_f32_32x32x16_bf16 v[80:95], v[222:225], v[110:113], v[80:95]
	v_exp_f32_e32 v203, v203
	v_exp_f32_e32 v204, v204
	v_exp_f32_e32 v205, v205
	s_waitcnt lgkmcnt(2)
	v_mfma_f32_32x32x16_bf16 v[64:79], v[226:229], v[110:113], v[64:79]
	ds_read_b128 v[222:225], v231 offset:16512
	ds_read_b128 v[226:229], v231 offset:24704
	v_exp_f32_e32 v206, v206
	v_exp_f32_e32 v207, v207
	v_exp_f32_e32 v210, v210
	s_waitcnt lgkmcnt(3)
	v_mfma_f32_32x32x16_bf16 v[80:95], v[214:217], v[106:109], v[80:95]
	v_add_u32_e32 v242, 0x4000, v240
	s_mov_b64 s[0:1], 0x1bc00000
	v_lshl_add_u64 v[238:239], v[156:157], 0, s[0:1]
	v_readfirstlane_b32 s2, v242
	s_mov_b32 m0, s2
	v_exp_f32_e32 v211, v211
	global_load_lds_dwordx4 v[238:239], off
	s_waitcnt lgkmcnt(2)
	v_mfma_f32_32x32x16_bf16 v[64:79], v[218:221], v[106:109], v[64:79]
	ds_read_b128 v[214:217], v234 offset:16512
	ds_read_b128 v[218:221], v234 offset:24704
	v_exp_f32_e32 v212, v212
	v_exp_f32_e32 v235, v208
	v_exp_f32_e32 v237, v197
	s_waitcnt lgkmcnt(3)
	v_mfma_f32_32x32x16_bf16 v[80:95], v[222:225], v[102:105], v[80:95]
	v_add_f32_e32 v197, 0, v194
	v_add_f32_e32 v197, v196, v197
	v_add_f32_e32 v197, v192, v197
	v_add_f32_e32 v197, v195, v197
	v_add_f32_e32 v197, v187, v197
	v_add_f32_e32 v197, v193, v197
	s_waitcnt lgkmcnt(2)
	v_mfma_f32_32x32x16_bf16 v[64:79], v[226:229], v[102:105], v[64:79]
	ds_read_b128 v[222:225], v213 offset:32768
	ds_read_b128 v[226:229], v213 offset:36864
	v_add_u32_e32 v213, s6, v183
	v_add_f32_e32 v197, v169, v197
	v_add_f32_e32 v197, v190, v197
	v_add_f32_e32 v197, v166, v197
	v_add_f32_e32 v197, v168, v197
	v_add_f32_e32 v197, v164, v197
	s_waitcnt lgkmcnt(3)
; #define SBAR() __builtin_amdgcn_sched_barrier(0)
; template <int OFF> DI s16x4 tr_read(int vb) { s16x4 r; asm volatile("ds_read_b64_tr_b16 %0, %1 offset:%2" : "=&v"(r) : "v"(vb), "i"(OFF) : "memory"); return r; }
; DI void finishSM(f32x16& p0, f32x16& p1, float alpha, float& l_reg, bf16x8& pa0, bf16x8& pa1, bf16x8& pa2, bf16x8& pa3) {
; #pragma unroll
;   for (int r = 0; r < 16; ++r) p1[r] = __builtin_amdgcn_exp2f(p1[r]);
;   float ps = 0;
; #pragma unroll
;   for (int r = 0; r < 16; ++r) ps += p0[r];
; #pragma unroll
;   for (int r = 0; r < 16; ++r) ps += p1[r];
;   { auto rr = __builtin_amdgcn_permlane32_swap(__float_as_uint(ps), __float_as_uint(ps), false, false);
;     ps = __uint_as_float(rr[0]) + __uint_as_float(rr[1]); }
;   l_reg = l_reg * alpha + ps;
;     ...
;   PK4(p0, 0, pa0); PK4(p0, 8, pa1); PK4(p1, 0, pa2); PK4(p1, 8, pa3);
; template <int D0> DI void pv_one(f32x16& od, int vb, bf16x8 pa0, bf16x8 pa1, bf16x8 pa2, bf16x8 pa3) {
;   const s16x4 l0 = tr_read<v_rd_off(D0, 0, 0)>(vb), h0 = tr_read<v_rd_off(D0, 0, 1)>(vb), l1 = tr_read<v_rd_off(D0, 1, 0)>(vb), h1 = tr_read<v_rd_off(D0, 1, 1)>(vb);
;   const s16x4 l2 = tr_read<v_rd_off(D0, 2, 0)>(vb), h2 = tr_read<v_rd_off(D0, 2, 1)>(vb), l3 = tr_read<v_rd_off(D0, 3, 0)>(vb), h3 = tr_read<v_rd_off(D0, 3, 1)>(vb);
;   asm volatile("s_waitcnt lgkmcnt(0)" ::: "memory"); SBAR();
;     ...
;   od = __builtin_amdgcn_mfma_f32_32x32x16_bf16(pa0, PK(l0, h0), od, 0, 0, 0);
;   od = __builtin_amdgcn_mfma_f32_32x32x16_bf16(pa1, PK(l1, h1), od, 0, 0, 0);
;   od = __builtin_amdgcn_mfma_f32_32x32x16_bf16(pa2, PK(l2, h2), od, 0, 0, 0);
;   od = __builtin_amdgcn_mfma_f32_32x32x16_bf16(pa3, PK(l3, h3), od, 0, 0, 0);
;     ...
; }
; DI void pv_d0(f32x16* o, int vb, bf16x8 pa0, bf16x8 pa1, bf16x8 pa2, bf16x8 pa3) {
;   pv_one<0>(o[0], vb, pa0, pa1, pa2, pa3); pv_one<1>(o[1], vb, pa0, pa1, pa2, pa3); pv_one<2>(o[2], vb, pa0, pa1, pa2, pa3); pv_one<3>(o[3], vb, pa0, pa1, pa2, pa3);
	v_mfma_f32_32x32x16_bf16 v[80:95], v[214:217], v[98:101], v[80:95]
	v_add_u32_e32 v242, 0x6000, v240
	s_mov_b64 s[0:1], 0x1bc20000
	v_lshl_add_u64 v[238:239], v[156:157], 0, s[0:1]
	v_readfirstlane_b32 s2, v242
	s_mov_b32 m0, s2
	v_add_f32_e32 v197, v167, v197
	global_load_lds_dwordx4 v[238:239], off
	v_add_f32_e32 v197, v162, v197
	v_add_f32_e32 v197, v165, v197
	s_waitcnt lgkmcnt(2)
	v_mfma_f32_32x32x16_bf16 v[64:79], v[218:221], v[98:101], v[64:79]
	ds_read_b128 v[214:217], v213 offset:32768
	ds_read_b128 v[218:221], v213 offset:36864
	v_add_u32_e32 v213, s6, v184
	v_add_f32_e32 v197, v161, v197
	v_add_f32_e32 v197, v163, v197
	v_add_f32_e32 v197, v198, v197
	v_add_f32_e32 v197, v199, v197
	v_add_f32_e32 v197, v200, v197
	s_waitcnt lgkmcnt(3)
	v_mfma_f32_32x32x16_bf16 v[80:95], v[222:225], v[122:125], v[80:95]
	v_add_f32_e32 v197, v201, v197
	v_add_f32_e32 v197, v202, v197
	v_add_f32_e32 v197, v203, v197
	v_add_f32_e32 v197, v204, v197
	v_exp_f32_e32 v241, v209
	s_waitcnt lgkmcnt(2)
	v_mfma_f32_32x32x16_bf16 v[64:79], v[226:229], v[122:125], v[64:79]
	ds_read_b128 v[222:225], v213 offset:32768
	ds_read_b128 v[226:229], v213 offset:36864
	v_add_u32_e32 v213, s6, v185
	v_add_f32_e32 v197, v205, v197
	v_add_f32_e32 v197, v206, v197
	v_add_f32_e32 v197, v207, v197
	v_add_f32_e32 v197, v235, v197
	v_add_f32_e32 v197, v241, v197
	s_waitcnt lgkmcnt(3)
	v_mfma_f32_32x32x16_bf16 v[80:95], v[214:217], v[142:145], v[80:95]
	v_add_u32_e32 v242, 0x8000, v240
	s_mov_b64 s[0:1], 0x1fb46000
	v_lshl_add_u64 v[238:239], v[154:155], 0, s[0:1]
	v_readfirstlane_b32 s2, v242
	s_mov_b32 m0, s2
	v_add_f32_e32 v197, v210, v197
	global_load_lds_dwordx4 v[238:239], off
	s_movk_i32 s0, 0x410
	s_movk_i32 s1, 0x1800
	v_add_f32_e32 v197, v211, v197
	v_add_f32_e32 v197, v212, v197
	s_waitcnt lgkmcnt(2)
	v_mfma_f32_32x32x16_bf16 v[64:79], v[218:221], v[142:145], v[64:79]
	ds_read_b128 v[214:217], v213 offset:32768
	ds_read_b128 v[218:221], v213 offset:36864
	v_add_f32_e32 v208, v237, v197
	v_mov_b32_e32 v209, v208
	v_cvt_pk_bf16_f32 v194, v194, v196
	v_cvt_pk_bf16_f32 v195, v192, v195
	v_permlane32_swap_b32_e32 v208, v209
	v_cvt_pk_bf16_f32 v196, v187, v193
	s_waitcnt lgkmcnt(3)
	v_mfma_f32_32x32x16_bf16 v[80:95], v[222:225], v[118:121], v[80:95]
	v_cvt_pk_bf16_f32 v197, v169, v190
	v_cvt_pk_bf16_f32 v166, v166, v168
	v_cvt_pk_bf16_f32 v167, v164, v167
	v_cvt_pk_bf16_f32 v168, v162, v165
	v_cvt_pk_bf16_f32 v169, v161, v163
	v_cvt_pk_bf16_f32 v162, v198, v199
	s_waitcnt lgkmcnt(2)
	v_mfma_f32_32x32x16_bf16 v[64:79], v[226:229], v[118:121], v[64:79]
	v_cvt_pk_bf16_f32 v163, v200, v201
	v_cvt_pk_bf16_f32 v164, v202, v203
	v_cvt_pk_bf16_f32 v165, v204, v205
	v_cvt_pk_bf16_f32 v198, v206, v207
	v_cvt_pk_bf16_f32 v199, v235, v241
	v_cvt_pk_bf16_f32 v200, v210, v211
	s_waitcnt lgkmcnt(1)
	v_mfma_f32_32x32x16_bf16 v[80:95], v[214:217], v[138:141], v[80:95]
	v_cvt_pk_bf16_f32 v201, v212, v237
	v_permlane32_swap_b32_e32 v194, v196
	v_permlane32_swap_b32_e32 v195, v197
	v_permlane32_swap_b32_e32 v166, v168
	v_permlane32_swap_b32_e32 v167, v169
	v_permlane32_swap_b32_e32 v162, v164
	s_waitcnt lgkmcnt(0)
	v_mfma_f32_32x32x16_bf16 v[64:79], v[218:221], v[138:141], v[64:79]
	v_add_u32_e32 v161, s42, v174
	ds_read_b64_tr_b16 v[202:203], v161 offset:0
	ds_read_b64_tr_b16 v[204:205], v161 offset:0x800
	ds_read_b64_tr_b16 v[210:211], v161 offset:0x1000
	ds_read_b64_tr_b16 v[212:213], v161 offset:0x1800
	ds_read_b64_tr_b16 v[214:215], v161 offset:0x2000
	ds_read_b64_tr_b16 v[216:217], v161 offset:0x2800
	ds_read_b64_tr_b16 v[218:219], v161 offset:0x3000
	ds_read_b64_tr_b16 v[220:221], v161 offset:0x3800
	v_permlane32_swap_b32_e32 v163, v165
	v_permlane32_swap_b32_e32 v198, v200
	v_permlane32_swap_b32_e32 v199, v201
	v_max_f32_e32 v235, v81, v81
	v_max_f32_e32 v237, v80, v80
	s_waitcnt lgkmcnt(6)
	v_mfma_f32_32x32x16_bf16 v[0:15], v[194:197], v[202:205], v[0:15]
	ds_read_b64_tr_b16 v[202:203], v161 offset:0x200
	ds_read_b64_tr_b16 v[204:205], v161 offset:0xa00
	v_max_f32_e32 v235, v237, v235
	v_max3_f32 v235, v235, v82, v83
	v_max3_f32 v235, v235, v84, v85
	v_max3_f32 v235, v235, v86, v87
	v_max3_f32 v235, v235, v88, v89
	v_max3_f32 v235, v235, v90, v91
	s_waitcnt lgkmcnt(6)
	v_mfma_f32_32x32x16_bf16 v[0:15], v[166:169], v[210:213], v[0:15]
	ds_read_b64_tr_b16 v[210:211], v161 offset:0x1200
	ds_read_b64_tr_b16 v[212:213], v161 offset:0x1a00
	v_max3_f32 v235, v235, v92, v93
	v_max3_f32 v235, v235, v94, v95
	v_max3_f32 v235, v235, v64, v65
	v_max3_f32 v235, v235, v66, v67
	v_max3_f32 v235, v235, v68, v69
	v_max3_f32 v235, v235, v70, v71
	s_waitcnt lgkmcnt(6)
	v_mfma_f32_32x32x16_bf16 v[0:15], v[162:165], v[214:217], v[0:15]
	ds_read_b64_tr_b16 v[214:215], v161 offset:0x2200
	ds_read_b64_tr_b16 v[216:217], v161 offset:0x2a00
	v_max3_f32 v235, v235, v72, v73
	v_max3_f32 v235, v235, v74, v75
	v_max3_f32 v235, v235, v76, v77
	v_max3_f32 v235, v235, v78, v79
	v_mov_b32_e32 v237, v235
	s_waitcnt lgkmcnt(6)
	v_mfma_f32_32x32x16_bf16 v[0:15], v[198:201], v[218:221], v[0:15]
	ds_read_b64_tr_b16 v[218:219], v161 offset:0x3200
	ds_read_b64_tr_b16 v[220:221], v161 offset:0x3a00
	v_permlane32_swap_b32_e32 v235, v237
	v_max_f32_e32 v237, v237, v237
	v_max_f32_e32 v235, v235, v235
	s_waitcnt lgkmcnt(6)
	v_mfma_f32_32x32x16_bf16 v[48:63], v[194:197], v[202:205], v[48:63]
	ds_read_b64_tr_b16 v[202:203], v161 offset:0x400
	ds_read_b64_tr_b16 v[204:205], v161 offset:0xc00
	s_waitcnt lgkmcnt(6)
	v_mfma_f32_32x32x16_bf16 v[48:63], v[166:169], v[210:213], v[48:63]
	ds_read_b64_tr_b16 v[210:211], v161 offset:0x1400
	ds_read_b64_tr_b16 v[212:213], v161 offset:0x1c00
	s_waitcnt lgkmcnt(6)
; #define SBAR() __builtin_amdgcn_sched_barrier(0)
; DI void partialSM(f32x16& p0, f32x16& p1, float& m_reg, float& mn, float& alpha) {
;   constexpr float C = ATT_SCALE * 1.4426950408889634f;
;   float pmax = p0[0];
; #pragma unroll
;   for (int r = 1; r < 16; ++r) pmax = fmaxf(pmax, p0[r]);
; #pragma unroll
;   for (int r = 0; r < 16; ++r) pmax = fmaxf(pmax, p1[r]);
;   { auto rr = __builtin_amdgcn_permlane32_swap(__float_as_uint(pmax), __float_as_uint(pmax), false, false);
;     pmax = fmaxf(__uint_as_float(rr[0]), __uint_as_float(rr[1])); }
;   if (__builtin_expect(__all(pmax - m_reg <= ATT_THR / ATT_SCALE), 1)) { mn = m_reg; alpha = 1.f; }
;   else { mn = fmaxf(m_reg, pmax); alpha = __builtin_amdgcn_exp2f((m_reg - mn) * C); m_reg = mn; }
;   const float mnC = -mn * C;
; #pragma unroll
;   for (int r = 0; r < 16; ++r) p0[r] = fmaf(p0[r], C, mnC);
; #pragma unroll
;   for (int r = 0; r < 16; ++r) p1[r] = fmaf(p1[r], C, mnC);
; #pragma unroll
;   for (int r = 0; r < 16; ++r) p0[r] = __builtin_amdgcn_exp2f(p0[r]);
; }
; DI void finishSM(f32x16& p0, f32x16& p1, float alpha, float& l_reg, bf16x8& pa0, bf16x8& pa1, bf16x8& pa2, bf16x8& pa3) {
; #pragma unroll
;   for (int r = 0; r < 16; ++r) p1[r] = __builtin_amdgcn_exp2f(p1[r]);
; template <int D0> DI void pv_one(f32x16& od, int vb, bf16x8 pa0, bf16x8 pa1, bf16x8 pa2, bf16x8 pa3) {
;   const s16x4 l0 = tr_read<v_rd_off(D0, 0, 0)>(vb), h0 = tr_read<v_rd_off(D0, 0, 1)>(vb), l1 = tr_read<v_rd_off(D0, 1, 0)>(vb), h1 = tr_read<v_rd_off(D0, 1, 1)>(vb);
;   const s16x4 l2 = tr_read<v_rd_off(D0, 2, 0)>(vb), h2 = tr_read<v_rd_off(D0, 2, 1)>(vb), l3 = tr_read<v_rd_off(D0, 3, 0)>(vb), h3 = tr_read<v_rd_off(D0, 3, 1)>(vb);
;   asm volatile("s_waitcnt lgkmcnt(0)" ::: "memory"); SBAR();
;     ...
;   od = __builtin_amdgcn_mfma_f32_32x32x16_bf16(pa0, PK(l0, h0), od, 0, 0, 0);
;   od = __builtin_amdgcn_mfma_f32_32x32x16_bf16(pa1, PK(l1, h1), od, 0, 0, 0);
;   od = __builtin_amdgcn_mfma_f32_32x32x16_bf16(pa2, PK(l2, h2), od, 0, 0, 0);
;   od = __builtin_amdgcn_mfma_f32_32x32x16_bf16(pa3, PK(l3, h3), od, 0, 0, 0);
;     ...
; }
; DI void pv_d0(f32x16* o, int vb, bf16x8 pa0, bf16x8 pa1, bf16x8 pa2, bf16x8 pa3) {
;   pv_one<0>(o[0], vb, pa0, pa1, pa2, pa3); pv_one<1>(o[1], vb, pa0, pa1, pa2, pa3); pv_one<2>(o[2], vb, pa0, pa1, pa2, pa3); pv_one<3>(o[3], vb, pa0, pa1, pa2, pa3);
	v_mfma_f32_32x32x16_bf16 v[48:63], v[162:165], v[214:217], v[48:63]
	ds_read_b64_tr_b16 v[214:215], v161 offset:0x2400
	ds_read_b64_tr_b16 v[216:217], v161 offset:0x2c00
	s_waitcnt lgkmcnt(6)
	v_mfma_f32_32x32x16_bf16 v[48:63], v[198:201], v[218:221], v[48:63]
	ds_read_b64_tr_b16 v[218:219], v161 offset:0x3400
	ds_read_b64_tr_b16 v[220:221], v161 offset:0x3c00
	s_waitcnt lgkmcnt(6)
	v_mfma_f32_32x32x16_bf16 v[32:47], v[194:197], v[202:205], v[32:47]
	ds_read_b64_tr_b16 v[202:203], v161 offset:0x600
	ds_read_b64_tr_b16 v[204:205], v161 offset:0xe00
	s_waitcnt lgkmcnt(6)
	v_mfma_f32_32x32x16_bf16 v[32:47], v[166:169], v[210:213], v[32:47]
	ds_read_b64_tr_b16 v[210:211], v161 offset:0x1600
	ds_read_b64_tr_b16 v[212:213], v161 offset:0x1e00
	s_waitcnt lgkmcnt(6)
	v_mfma_f32_32x32x16_bf16 v[32:47], v[162:165], v[214:217], v[32:47]
	ds_read_b64_tr_b16 v[214:215], v161 offset:0x2600
	ds_read_b64_tr_b16 v[216:217], v161 offset:0x2e00
	s_waitcnt lgkmcnt(6)
	v_mfma_f32_32x32x16_bf16 v[32:47], v[198:201], v[218:221], v[32:47]
	ds_read_b64_tr_b16 v[218:219], v161 offset:0x3600
	ds_read_b64_tr_b16 v[220:221], v161 offset:0x3e00
	v_max_f32_e32 v161, v235, v237
	v_sub_f32_e32 v237, v161, v160
	s_waitcnt lgkmcnt(6)
	v_mfma_f32_32x32x16_bf16 v[16:31], v[194:197], v[202:205], v[16:31]
	s_waitcnt lgkmcnt(4)
	v_mfma_f32_32x32x16_bf16 v[16:31], v[166:169], v[210:213], v[16:31]
	s_waitcnt lgkmcnt(2)
	v_mfma_f32_32x32x16_bf16 v[16:31], v[162:165], v[214:217], v[16:31]
	s_waitcnt lgkmcnt(0)
	v_mfma_f32_32x32x16_bf16 v[16:31], v[198:201], v[218:221], v[16:31]
	v_cmp_ge_f32_e32 vcc, s65, v237
	s_cmp_eq_u64 vcc, exec
	s_cselect_b64 s[38:39], -1, 0
	s_cmp_ge_u32 s12, s52
	s_cselect_b64 s[42:43], -1, 0
	s_and_b64 vcc, exec, s[42:43]
	s_waitcnt vmcnt(0)
	s_waitcnt vmcnt(0)
	s_barrier
	s_branch .Lattn_bb2_join
.Lattn_bb2_nodma:
	v_cndmask_b32_e64 v160, v160, v187, s[38:39]
	s_add_i32 s2, s42, 0xa000
	s_cmp_lg_u32 s61, 2
	s_cselect_b32 s2, s2, 0
	s_add_i32 s6, s2, 16
	v_add_u32_e32 v213, s6, v176
	ds_read_b128 v[222:225], v213 offset:16384
	v_add_u32_e32 v230, s6, v179
	ds_read_b128 v[226:229], v213 offset:24576
	ds_read_b128 v[214:217], v230 offset:16384
	ds_read_b128 v[218:221], v230 offset:24576
	v_add_u32_e32 v231, s6, v180
	v_add_u32_e32 v234, s6, v181
	v_mul_f32_e32 v197, 0xbdd53b94, v160
	v_fmamk_f32 v161, v94, 0x3dd53b94, v197
	v_fmamk_f32 v194, v80, 0x3dd53b94, v197
	v_fmamk_f32 v196, v81, 0x3dd53b94, v197
	v_fmamk_f32 v192, v82, 0x3dd53b94, v197
	v_fmamk_f32 v195, v83, 0x3dd53b94, v197
	v_fmamk_f32 v187, v84, 0x3dd53b94, v197
	v_fmamk_f32 v193, v85, 0x3dd53b94, v197
	v_fmamk_f32 v169, v86, 0x3dd53b94, v197
	v_fmamk_f32 v190, v87, 0x3dd53b94, v197
	v_fmamk_f32 v166, v88, 0x3dd53b94, v197
	v_fmamk_f32 v168, v89, 0x3dd53b94, v197
	v_fmamk_f32 v164, v90, 0x3dd53b94, v197
	v_fmamk_f32 v167, v91, 0x3dd53b94, v197
	v_fmamk_f32 v162, v92, 0x3dd53b94, v197
	v_fmamk_f32 v165, v93, 0x3dd53b94, v197
	v_fmamk_f32 v163, v95, 0x3dd53b94, v197
	v_fmamk_f32 v208, v74, 0x3dd53b94, v197
	v_fmamk_f32 v209, v75, 0x3dd53b94, v197
	v_fmamk_f32 v198, v64, 0x3dd53b94, v197
	v_fmamk_f32 v199, v65, 0x3dd53b94, v197
	v_fmamk_f32 v200, v66, 0x3dd53b94, v197
	v_fmamk_f32 v201, v67, 0x3dd53b94, v197
	v_fmamk_f32 v202, v68, 0x3dd53b94, v197
	v_fmamk_f32 v203, v69, 0x3dd53b94, v197
	v_fmamk_f32 v204, v70, 0x3dd53b94, v197
	v_fmamk_f32 v205, v71, 0x3dd53b94, v197
	v_fmamk_f32 v206, v72, 0x3dd53b94, v197
	v_fmamk_f32 v207, v73, 0x3dd53b94, v197
	v_fmamk_f32 v210, v76, 0x3dd53b94, v197
	v_fmamk_f32 v211, v77, 0x3dd53b94, v197
	v_fmamk_f32 v212, v78, 0x3dd53b94, v197
	v_fmac_f32_e32 v197, 0x3dd53b94, v79
	v_exp_f32_e32 v161, v161
	s_waitcnt lgkmcnt(3)
	v_mfma_f32_32x32x16_bf16 v[80:95], v[222:225], v[134:137], 0
	v_exp_f32_e32 v194, v194
	v_exp_f32_e32 v196, v196
	v_exp_f32_e32 v192, v192
	s_waitcnt lgkmcnt(2)
	v_mfma_f32_32x32x16_bf16 v[64:79], v[226:229], v[134:137], 0
	ds_read_b128 v[222:225], v231 offset:16384
	ds_read_b128 v[226:229], v231 offset:24576
	v_exp_f32_e32 v195, v195
	v_exp_f32_e32 v187, v187
	v_exp_f32_e32 v193, v193
	s_waitcnt lgkmcnt(3)
	v_mfma_f32_32x32x16_bf16 v[80:95], v[214:217], v[130:133], v[80:95]
	v_exp_f32_e32 v169, v169
	v_exp_f32_e32 v190, v190
	v_exp_f32_e32 v166, v166
	s_waitcnt lgkmcnt(2)
	v_mfma_f32_32x32x16_bf16 v[64:79], v[218:221], v[130:133], v[64:79]
	ds_read_b128 v[214:217], v234 offset:16384
	ds_read_b128 v[218:221], v234 offset:24576
	v_exp_f32_e32 v168, v168
	v_exp_f32_e32 v164, v164
	v_exp_f32_e32 v167, v167
	s_waitcnt lgkmcnt(3)
	v_mfma_f32_32x32x16_bf16 v[80:95], v[222:225], v[126:129], v[80:95]
	v_exp_f32_e32 v162, v162
	v_exp_f32_e32 v165, v165
	v_exp_f32_e32 v163, v163
	s_waitcnt lgkmcnt(2)
	v_mfma_f32_32x32x16_bf16 v[64:79], v[226:229], v[126:129], v[64:79]
	ds_read_b128 v[222:225], v213 offset:16512
	ds_read_b128 v[226:229], v213 offset:24704
	v_add_u32_e32 v213, s6, v182
	v_exp_f32_e32 v198, v198
	v_exp_f32_e32 v199, v199
	s_waitcnt lgkmcnt(3)
	v_mfma_f32_32x32x16_bf16 v[80:95], v[214:217], v[114:117], v[80:95]
	v_exp_f32_e32 v200, v200
	v_exp_f32_e32 v201, v201
	v_exp_f32_e32 v202, v202
	s_waitcnt lgkmcnt(2)
	v_mfma_f32_32x32x16_bf16 v[64:79], v[218:221], v[114:117], v[64:79]
	ds_read_b128 v[214:217], v230 offset:16512
	ds_read_b128 v[218:221], v230 offset:24704
	v_exp_f32_e32 v203, v203
	v_exp_f32_e32 v204, v204
	v_exp_f32_e32 v205, v205
	s_waitcnt lgkmcnt(3)
	v_mfma_f32_32x32x16_bf16 v[80:95], v[222:225], v[110:113], v[80:95]
	v_exp_f32_e32 v206, v206
	v_exp_f32_e32 v207, v207
	v_exp_f32_e32 v210, v210
	s_waitcnt lgkmcnt(2)
; #define QK_FENCE() __builtin_amdgcn_sched_barrier(0x406)
; DI void finishSM(f32x16& p0, f32x16& p1, float alpha, float& l_reg, bf16x8& pa0, bf16x8& pa1, bf16x8& pa2, bf16x8& pa3) {
; #pragma unroll
;   for (int r = 0; r < 16; ++r) p1[r] = __builtin_amdgcn_exp2f(p1[r]);
;   float ps = 0;
; #pragma unroll
;   for (int r = 0; r < 16; ++r) ps += p0[r];
; #pragma unroll
;   for (int r = 0; r < 16; ++r) ps += p1[r];
;   { auto rr = __builtin_amdgcn_permlane32_swap(__float_as_uint(ps), __float_as_uint(ps), false, false);
;     ps = __uint_as_float(rr[0]) + __uint_as_float(rr[1]); }
;   l_reg = l_reg * alpha + ps;
;     ...
;   PK4(p0, 0, pa0); PK4(p0, 8, pa1); PK4(p1, 0, pa2); PK4(p1, 8, pa3);
; DI void qkt12(f32x16& p0, f32x16& p1, const char* Kt, const char* Rt, const int* ko, const int* ro, const bf16x8* qr) {
;   { const f32x16 z = {0.f, 0.f, 0.f, 0.f, 0.f, 0.f, 0.f, 0.f, 0.f, 0.f, 0.f, 0.f, 0.f, 0.f, 0.f, 0.f}; p0 = z; p1 = z; }
;   const char* kp[4] = {Kt + ko[0], Kt + ko[1], Kt + ko[2], Kt + ko[3]};
;   const char* rp[4] = {Rt + ro[0], Rt + ro[1], Rt + ro[2], Rt + ro[3]};
;   bf16x8 ka[2], kb[2];
;   ka[0] = *reinterpret_cast<const bf16x8*>(kp[0]); kb[0] = *reinterpret_cast<const bf16x8*>(kp[0] + 8192);
; #pragma unroll
;   for (int d0 = 0; d0 < 12; ++d0) {
;     if (d0 + 1 < 12) { const int d1 = d0 + 1;
;       if (d1 < 8) { ka[d1 & 1] = *reinterpret_cast<const bf16x8*>(kp[d1 & 3] + (d1 >> 2) * 128); kb[d1 & 1] = *reinterpret_cast<const bf16x8*>(kp[d1 & 3] + (d1 >> 2) * 128 + 8192); }
;       else { ka[d1 & 1] = *reinterpret_cast<const bf16x8*>(rp[d1 - 8]); kb[d1 & 1] = *reinterpret_cast<const bf16x8*>(rp[d1 - 8] + 4096); } }
;     QK_FENCE();
;     p0 = __builtin_amdgcn_mfma_f32_32x32x16_bf16(ka[d0 & 1], qr[d0], p0, 0, 0, 0);
;     p1 = __builtin_amdgcn_mfma_f32_32x32x16_bf16(kb[d0 & 1], qr[d0], p1, 0, 0, 0);
;     QK_FENCE();
;   }
	v_mfma_f32_32x32x16_bf16 v[64:79], v[226:229], v[110:113], v[64:79]
	ds_read_b128 v[222:225], v231 offset:16512
	ds_read_b128 v[226:229], v231 offset:24704
	v_exp_f32_e32 v211, v211
	v_exp_f32_e32 v212, v212
	v_exp_f32_e32 v235, v208
	s_waitcnt lgkmcnt(3)
	v_mfma_f32_32x32x16_bf16 v[80:95], v[214:217], v[106:109], v[80:95]
	v_exp_f32_e32 v237, v197
	v_add_f32_e32 v197, 0, v194
	v_add_f32_e32 v197, v196, v197
	v_add_f32_e32 v197, v192, v197
	v_add_f32_e32 v197, v195, v197
	s_waitcnt lgkmcnt(2)
	v_mfma_f32_32x32x16_bf16 v[64:79], v[218:221], v[106:109], v[64:79]
	ds_read_b128 v[214:217], v234 offset:16512
	ds_read_b128 v[218:221], v234 offset:24704
	v_add_f32_e32 v197, v187, v197
	v_add_f32_e32 v197, v193, v197
	v_add_f32_e32 v197, v169, v197
	v_add_f32_e32 v197, v190, v197
	v_add_f32_e32 v197, v166, v197
	v_add_f32_e32 v197, v168, v197
	s_waitcnt lgkmcnt(3)
	v_mfma_f32_32x32x16_bf16 v[80:95], v[222:225], v[102:105], v[80:95]
	v_add_f32_e32 v197, v164, v197
	v_add_f32_e32 v197, v167, v197
	v_add_f32_e32 v197, v162, v197
	v_add_f32_e32 v197, v165, v197
	v_add_f32_e32 v197, v161, v197
	v_add_f32_e32 v197, v163, v197
	s_waitcnt lgkmcnt(2)
	v_mfma_f32_32x32x16_bf16 v[64:79], v[226:229], v[102:105], v[64:79]
	ds_read_b128 v[222:225], v213 offset:32768
	ds_read_b128 v[226:229], v213 offset:36864
	v_add_u32_e32 v213, s6, v183
	v_add_f32_e32 v197, v198, v197
	v_add_f32_e32 v197, v199, v197
	v_add_f32_e32 v197, v200, v197
	v_add_f32_e32 v197, v201, v197
	v_add_f32_e32 v197, v202, v197
	s_waitcnt lgkmcnt(3)
	v_mfma_f32_32x32x16_bf16 v[80:95], v[214:217], v[98:101], v[80:95]
	v_add_f32_e32 v197, v203, v197
	v_add_f32_e32 v197, v204, v197
	v_exp_f32_e32 v241, v209
	v_add_f32_e32 v197, v205, v197
	v_add_f32_e32 v197, v206, v197
	s_waitcnt lgkmcnt(2)
	v_mfma_f32_32x32x16_bf16 v[64:79], v[218:221], v[98:101], v[64:79]
	ds_read_b128 v[214:217], v213 offset:32768
	ds_read_b128 v[218:221], v213 offset:36864
	v_add_u32_e32 v213, s6, v184
	v_add_f32_e32 v197, v207, v197
	v_add_f32_e32 v197, v235, v197
	v_add_f32_e32 v197, v241, v197
	v_add_f32_e32 v197, v210, v197
	v_add_f32_e32 v197, v211, v197
	s_waitcnt lgkmcnt(3)
	v_mfma_f32_32x32x16_bf16 v[80:95], v[222:225], v[122:125], v[80:95]
	v_add_f32_e32 v197, v212, v197
	v_add_f32_e32 v208, v237, v197
	v_mov_b32_e32 v209, v208
	v_cvt_pk_bf16_f32 v194, v194, v196
	v_cvt_pk_bf16_f32 v195, v192, v195
	v_permlane32_swap_b32_e32 v208, v209
	s_waitcnt lgkmcnt(2)
	v_mfma_f32_32x32x16_bf16 v[64:79], v[226:229], v[122:125], v[64:79]
	ds_read_b128 v[222:225], v213 offset:32768
	ds_read_b128 v[226:229], v213 offset:36864
	v_add_u32_e32 v213, s6, v185
	v_cvt_pk_bf16_f32 v196, v187, v193
	v_cvt_pk_bf16_f32 v197, v169, v190
	v_cvt_pk_bf16_f32 v166, v166, v168
	v_cvt_pk_bf16_f32 v167, v164, v167
	v_cvt_pk_bf16_f32 v168, v162, v165
	s_waitcnt lgkmcnt(3)
	v_mfma_f32_32x32x16_bf16 v[80:95], v[214:217], v[142:145], v[80:95]
	v_cvt_pk_bf16_f32 v169, v161, v163
	v_cvt_pk_bf16_f32 v162, v198, v199
	v_cvt_pk_bf16_f32 v163, v200, v201
	v_cvt_pk_bf16_f32 v164, v202, v203
	v_cvt_pk_bf16_f32 v165, v204, v205
	v_cvt_pk_bf16_f32 v198, v206, v207
	s_waitcnt lgkmcnt(2)
	v_mfma_f32_32x32x16_bf16 v[64:79], v[218:221], v[142:145], v[64:79]
	ds_read_b128 v[214:217], v213 offset:32768
	ds_read_b128 v[218:221], v213 offset:36864
	v_cvt_pk_bf16_f32 v199, v235, v241
	v_cvt_pk_bf16_f32 v200, v210, v211
	v_cvt_pk_bf16_f32 v201, v212, v237
	v_permlane32_swap_b32_e32 v194, v196
	v_permlane32_swap_b32_e32 v195, v197
	v_permlane32_swap_b32_e32 v166, v168
	s_waitcnt lgkmcnt(3)
	v_mfma_f32_32x32x16_bf16 v[80:95], v[222:225], v[118:121], v[80:95]
	v_permlane32_swap_b32_e32 v167, v169
	v_permlane32_swap_b32_e32 v162, v164
	v_permlane32_swap_b32_e32 v163, v165
	v_permlane32_swap_b32_e32 v198, v200
	v_permlane32_swap_b32_e32 v199, v201
	s_waitcnt lgkmcnt(2)
	v_mfma_f32_32x32x16_bf16 v[64:79], v[226:229], v[118:121], v[64:79]
	s_waitcnt lgkmcnt(1)
	v_mfma_f32_32x32x16_bf16 v[80:95], v[214:217], v[138:141], v[80:95]
	s_waitcnt lgkmcnt(0)
; #define SBAR() __builtin_amdgcn_sched_barrier(0)
; template <int OFF> DI s16x4 tr_read(int vb) { s16x4 r; asm volatile("ds_read_b64_tr_b16 %0, %1 offset:%2" : "=&v"(r) : "v"(vb), "i"(OFF) : "memory"); return r; }
; DI void partialSM(f32x16& p0, f32x16& p1, float& m_reg, float& mn, float& alpha) {
;   constexpr float C = ATT_SCALE * 1.4426950408889634f;
;   float pmax = p0[0];
; #pragma unroll
;   for (int r = 1; r < 16; ++r) pmax = fmaxf(pmax, p0[r]);
; #pragma unroll
;   for (int r = 0; r < 16; ++r) pmax = fmaxf(pmax, p1[r]);
;   { auto rr = __builtin_amdgcn_permlane32_swap(__float_as_uint(pmax), __float_as_uint(pmax), false, false);
;     pmax = fmaxf(__uint_as_float(rr[0]), __uint_as_float(rr[1])); }
;   if (__builtin_expect(__all(pmax - m_reg <= ATT_THR / ATT_SCALE), 1)) { mn = m_reg; alpha = 1.f; }
; template <int D0> DI void pv_one(f32x16& od, int vb, bf16x8 pa0, bf16x8 pa1, bf16x8 pa2, bf16x8 pa3) {
;   const s16x4 l0 = tr_read<v_rd_off(D0, 0, 0)>(vb), h0 = tr_read<v_rd_off(D0, 0, 1)>(vb), l1 = tr_read<v_rd_off(D0, 1, 0)>(vb), h1 = tr_read<v_rd_off(D0, 1, 1)>(vb);
;   const s16x4 l2 = tr_read<v_rd_off(D0, 2, 0)>(vb), h2 = tr_read<v_rd_off(D0, 2, 1)>(vb), l3 = tr_read<v_rd_off(D0, 3, 0)>(vb), h3 = tr_read<v_rd_off(D0, 3, 1)>(vb);
;   asm volatile("s_waitcnt lgkmcnt(0)" ::: "memory"); SBAR();
;     ...
;   od = __builtin_amdgcn_mfma_f32_32x32x16_bf16(pa0, PK(l0, h0), od, 0, 0, 0);
;   od = __builtin_amdgcn_mfma_f32_32x32x16_bf16(pa1, PK(l1, h1), od, 0, 0, 0);
;   od = __builtin_amdgcn_mfma_f32_32x32x16_bf16(pa2, PK(l2, h2), od, 0, 0, 0);
;   od = __builtin_amdgcn_mfma_f32_32x32x16_bf16(pa3, PK(l3, h3), od, 0, 0, 0);
;     ...
; }
; DI void pv_d0(f32x16* o, int vb, bf16x8 pa0, bf16x8 pa1, bf16x8 pa2, bf16x8 pa3) {
;   pv_one<0>(o[0], vb, pa0, pa1, pa2, pa3); pv_one<1>(o[1], vb, pa0, pa1, pa2, pa3); pv_one<2>(o[2], vb, pa0, pa1, pa2, pa3); pv_one<3>(o[3], vb, pa0, pa1, pa2, pa3);
	v_mfma_f32_32x32x16_bf16 v[64:79], v[218:221], v[138:141], v[64:79]
	v_add_u32_e32 v161, s42, v174
	ds_read_b64_tr_b16 v[202:203], v161 offset:0
	ds_read_b64_tr_b16 v[204:205], v161 offset:0x800
	ds_read_b64_tr_b16 v[210:211], v161 offset:0x1000
	ds_read_b64_tr_b16 v[212:213], v161 offset:0x1800
	ds_read_b64_tr_b16 v[214:215], v161 offset:0x2000
	ds_read_b64_tr_b16 v[216:217], v161 offset:0x2800
	ds_read_b64_tr_b16 v[218:219], v161 offset:0x3000
	ds_read_b64_tr_b16 v[220:221], v161 offset:0x3800
	s_waitcnt lgkmcnt(6)
	v_max_f32_e32 v235, v81, v81
	v_max_f32_e32 v237, v80, v80
	v_max_f32_e32 v235, v237, v235
	v_max3_f32 v235, v235, v82, v83
	v_max3_f32 v235, v235, v84, v85
	v_mfma_f32_32x32x16_bf16 v[0:15], v[194:197], v[202:205], v[0:15]
	ds_read_b64_tr_b16 v[202:203], v161 offset:0x200
	ds_read_b64_tr_b16 v[204:205], v161 offset:0xa00
	v_max3_f32 v235, v235, v86, v87
	v_max3_f32 v235, v235, v88, v89
	v_max3_f32 v235, v235, v90, v91
	v_max3_f32 v235, v235, v92, v93
	v_max3_f32 v235, v235, v94, v95
	v_max3_f32 v235, v235, v64, v65
	s_waitcnt lgkmcnt(6)
	v_mfma_f32_32x32x16_bf16 v[0:15], v[166:169], v[210:213], v[0:15]
	ds_read_b64_tr_b16 v[210:211], v161 offset:0x1200
	ds_read_b64_tr_b16 v[212:213], v161 offset:0x1a00
	v_max3_f32 v235, v235, v66, v67
	v_max3_f32 v235, v235, v68, v69
	v_max3_f32 v235, v235, v70, v71
	v_max3_f32 v235, v235, v72, v73
	v_max3_f32 v235, v235, v74, v75
	v_max3_f32 v235, v235, v76, v77
	s_waitcnt lgkmcnt(6)
	v_mfma_f32_32x32x16_bf16 v[0:15], v[162:165], v[214:217], v[0:15]
	ds_read_b64_tr_b16 v[214:215], v161 offset:0x2200
	ds_read_b64_tr_b16 v[216:217], v161 offset:0x2a00
	v_max3_f32 v235, v235, v78, v79
	v_mov_b32_e32 v237, v235
	s_waitcnt lgkmcnt(6)
	v_mfma_f32_32x32x16_bf16 v[0:15], v[198:201], v[218:221], v[0:15]
	ds_read_b64_tr_b16 v[218:219], v161 offset:0x3200
	ds_read_b64_tr_b16 v[220:221], v161 offset:0x3a00
	v_permlane32_swap_b32_e32 v235, v237
	v_max_f32_e32 v237, v237, v237
	v_max_f32_e32 v235, v235, v235
	s_waitcnt lgkmcnt(6)
	v_mfma_f32_32x32x16_bf16 v[48:63], v[194:197], v[202:205], v[48:63]
	ds_read_b64_tr_b16 v[202:203], v161 offset:0x400
	ds_read_b64_tr_b16 v[204:205], v161 offset:0xc00
	s_waitcnt lgkmcnt(6)
	v_mfma_f32_32x32x16_bf16 v[48:63], v[166:169], v[210:213], v[48:63]
	ds_read_b64_tr_b16 v[210:211], v161 offset:0x1400
	ds_read_b64_tr_b16 v[212:213], v161 offset:0x1c00
	s_waitcnt lgkmcnt(6)
	v_mfma_f32_32x32x16_bf16 v[48:63], v[162:165], v[214:217], v[48:63]
	ds_read_b64_tr_b16 v[214:215], v161 offset:0x2400
	ds_read_b64_tr_b16 v[216:217], v161 offset:0x2c00
	s_waitcnt lgkmcnt(6)
	v_mfma_f32_32x32x16_bf16 v[48:63], v[198:201], v[218:221], v[48:63]
	ds_read_b64_tr_b16 v[218:219], v161 offset:0x3400
	ds_read_b64_tr_b16 v[220:221], v161 offset:0x3c00
	s_waitcnt lgkmcnt(6)
	v_mfma_f32_32x32x16_bf16 v[32:47], v[194:197], v[202:205], v[32:47]
	ds_read_b64_tr_b16 v[202:203], v161 offset:0x600
	ds_read_b64_tr_b16 v[204:205], v161 offset:0xe00
	s_waitcnt lgkmcnt(6)
	v_mfma_f32_32x32x16_bf16 v[32:47], v[166:169], v[210:213], v[32:47]
	ds_read_b64_tr_b16 v[210:211], v161 offset:0x1600
	ds_read_b64_tr_b16 v[212:213], v161 offset:0x1e00
	s_waitcnt lgkmcnt(6)
	v_mfma_f32_32x32x16_bf16 v[32:47], v[162:165], v[214:217], v[32:47]
	ds_read_b64_tr_b16 v[214:215], v161 offset:0x2600
	ds_read_b64_tr_b16 v[216:217], v161 offset:0x2e00
	s_waitcnt lgkmcnt(6)
	v_mfma_f32_32x32x16_bf16 v[32:47], v[198:201], v[218:221], v[32:47]
	ds_read_b64_tr_b16 v[218:219], v161 offset:0x3600
	ds_read_b64_tr_b16 v[220:221], v161 offset:0x3e00
	v_max_f32_e32 v161, v235, v237
	v_sub_f32_e32 v237, v161, v160
	s_waitcnt lgkmcnt(6)
	v_mfma_f32_32x32x16_bf16 v[16:31], v[194:197], v[202:205], v[16:31]
	s_waitcnt lgkmcnt(4)
	v_mfma_f32_32x32x16_bf16 v[16:31], v[166:169], v[210:213], v[16:31]
	s_waitcnt lgkmcnt(2)
	v_mfma_f32_32x32x16_bf16 v[16:31], v[162:165], v[214:217], v[16:31]
	s_waitcnt lgkmcnt(0)
	v_mfma_f32_32x32x16_bf16 v[16:31], v[198:201], v[218:221], v[16:31]
	v_cmp_ge_f32_e32 vcc, s65, v237
	s_cmp_eq_u64 vcc, exec
	s_cselect_b64 s[38:39], -1, 0
	s_cmp_ge_u32 s12, s52
	s_cselect_b64 s[42:43], -1, 0
	s_and_b64 vcc, exec, s[42:43]
	s_waitcnt vmcnt(0)
	s_waitcnt vmcnt(0)
	s_barrier
